# also: oproj/down prompt-tile epilogue fast path (gate vector loaded once per tile, next row group's residual prefetched)
# speedup vs baseline: 1.0314x; 1.0008x over previous
.LBB0_1332:
	s_waitcnt vmcnt(0)
	v_lshlrev_b32_e32 v0, 2, v166
	s_waitcnt lgkmcnt(0)
	s_barrier
	s_waitcnt lgkmcnt(0)
	v_lshl_or_b32 v142, s15, 7, v167
	v_lshl_or_b32 v0, s14, 6, v0
	v_add_u32_e32 v134, s22, v142
	v_or_b32_e32 v0, s12, v0
	v_cmp_gt_i32_e32 vcc, s20, v134
	v_lshlrev_b32_e32 v0, 2, v0
	s_cmp_eq_u64 s[10:11], 0
	s_cbranch_scc1 .Lop0_orig
	s_lshr_b32 s0, s22, 12
	s_mul_i32 s0, s0, s17
	s_add_u32 s0, s6, s0
	s_addc_u32 s1, s7, 0
	v_readlane_b32 s36, v192, 37
	v_readlane_b32 s37, v192, 38
	global_load_dwordx4 v[194:197], v0, s[0:1] offset:0
	global_load_dwordx4 v[198:201], v0, s[0:1] offset:64
	global_load_dwordx4 v[202:205], v0, s[0:1] offset:128
	global_load_dwordx4 v[206:209], v0, s[0:1] offset:192
	v_lshlrev_b32_e32 v242, 12, v134
	v_add_u32_e32 v242, v242, v0
	v_mov_b32_e32 v243, v242
	global_load_dwordx4 v[210:213], v242, s[36:37] offset:0
	global_load_dwordx4 v[214:217], v242, s[36:37] offset:64
	global_load_dwordx4 v[218:221], v242, s[36:37] offset:128
	global_load_dwordx4 v[222:225], v242, s[36:37] offset:192
	v_add_u32_e32 v242, 0x10000, v242
	global_load_dwordx4 v[226:229], v242, s[36:37] offset:0
	global_load_dwordx4 v[230:233], v242, s[36:37] offset:64
	global_load_dwordx4 v[234:237], v242, s[36:37] offset:128
	global_load_dwordx4 v[238:241], v242, s[36:37] offset:192
	v_add_u32_e32 v242, 0x10000, v242
	s_waitcnt vmcnt(4)
	v_fma_f32 v126, v126, v194, v210
	v_fma_f32 v127, v127, v195, v211
	v_fma_f32 v128, v128, v196, v212
	v_fma_f32 v129, v129, v197, v213
	v_fma_f32 v122, v122, v198, v214
	v_fma_f32 v123, v123, v199, v215
	v_fma_f32 v124, v124, v200, v216
	v_fma_f32 v125, v125, v201, v217
	v_fma_f32 v118, v118, v202, v218
	v_fma_f32 v119, v119, v203, v219
	v_fma_f32 v120, v120, v204, v220
	v_fma_f32 v121, v121, v205, v221
	v_fma_f32 v114, v114, v206, v222
	v_fma_f32 v115, v115, v207, v223
	v_fma_f32 v116, v116, v208, v224
	v_fma_f32 v117, v117, v209, v225
	global_store_dwordx4 v243, v[126:129], s[82:83] offset:0
	global_store_dwordx4 v243, v[122:125], s[82:83] offset:64
	global_store_dwordx4 v243, v[118:121], s[82:83] offset:128
	global_store_dwordx4 v243, v[114:117], s[82:83] offset:192
	v_add_u32_e32 v243, 0x10000, v243
	global_load_dwordx4 v[210:213], v242, s[36:37] offset:0
	global_load_dwordx4 v[214:217], v242, s[36:37] offset:64
	global_load_dwordx4 v[218:221], v242, s[36:37] offset:128
	global_load_dwordx4 v[222:225], v242, s[36:37] offset:192
	v_add_u32_e32 v242, 0x10000, v242
	s_waitcnt vmcnt(8)
	v_fma_f32 v110, v110, v194, v226
	v_fma_f32 v111, v111, v195, v227
	v_fma_f32 v112, v112, v196, v228
	v_fma_f32 v113, v113, v197, v229
	v_fma_f32 v106, v106, v198, v230
	v_fma_f32 v107, v107, v199, v231
	v_fma_f32 v108, v108, v200, v232
	v_fma_f32 v109, v109, v201, v233
	v_fma_f32 v102, v102, v202, v234
	v_fma_f32 v103, v103, v203, v235
	v_fma_f32 v104, v104, v204, v236
	v_fma_f32 v105, v105, v205, v237
	v_fma_f32 v98, v98, v206, v238
	v_fma_f32 v99, v99, v207, v239
	v_fma_f32 v100, v100, v208, v240
	v_fma_f32 v101, v101, v209, v241
	global_store_dwordx4 v243, v[110:113], s[82:83] offset:0
	global_store_dwordx4 v243, v[106:109], s[82:83] offset:64
	global_store_dwordx4 v243, v[102:105], s[82:83] offset:128
	global_store_dwordx4 v243, v[98:101], s[82:83] offset:192
	v_add_u32_e32 v243, 0x10000, v243
	global_load_dwordx4 v[226:229], v242, s[36:37] offset:0
	global_load_dwordx4 v[230:233], v242, s[36:37] offset:64
	global_load_dwordx4 v[234:237], v242, s[36:37] offset:128
	global_load_dwordx4 v[238:241], v242, s[36:37] offset:192
	v_add_u32_e32 v242, 0x10000, v242
	s_waitcnt vmcnt(8)
	v_fma_f32 v94, v94, v194, v210
	v_fma_f32 v95, v95, v195, v211
	v_fma_f32 v96, v96, v196, v212
	v_fma_f32 v97, v97, v197, v213
	v_fma_f32 v90, v90, v198, v214
	v_fma_f32 v91, v91, v199, v215
	v_fma_f32 v92, v92, v200, v216
	v_fma_f32 v93, v93, v201, v217
	v_fma_f32 v86, v86, v202, v218
	v_fma_f32 v87, v87, v203, v219
	v_fma_f32 v88, v88, v204, v220
	v_fma_f32 v89, v89, v205, v221
	v_fma_f32 v82, v82, v206, v222
	v_fma_f32 v83, v83, v207, v223
	v_fma_f32 v84, v84, v208, v224
	v_fma_f32 v85, v85, v209, v225
	global_store_dwordx4 v243, v[94:97], s[82:83] offset:0
	global_store_dwordx4 v243, v[90:93], s[82:83] offset:64
	global_store_dwordx4 v243, v[86:89], s[82:83] offset:128
	global_store_dwordx4 v243, v[82:85], s[82:83] offset:192
	v_add_u32_e32 v243, 0x10000, v243
	global_load_dwordx4 v[210:213], v242, s[36:37] offset:0
	global_load_dwordx4 v[214:217], v242, s[36:37] offset:64
	global_load_dwordx4 v[218:221], v242, s[36:37] offset:128
	global_load_dwordx4 v[222:225], v242, s[36:37] offset:192
	v_add_u32_e32 v242, 0x10000, v242
	s_waitcnt vmcnt(8)
	v_fma_f32 v78, v78, v194, v226
	v_fma_f32 v79, v79, v195, v227
	v_fma_f32 v80, v80, v196, v228
	v_fma_f32 v81, v81, v197, v229
	v_fma_f32 v74, v74, v198, v230
	v_fma_f32 v75, v75, v199, v231
	v_fma_f32 v76, v76, v200, v232
	v_fma_f32 v77, v77, v201, v233
	v_fma_f32 v70, v70, v202, v234
	v_fma_f32 v71, v71, v203, v235
	v_fma_f32 v72, v72, v204, v236
	v_fma_f32 v73, v73, v205, v237
	v_fma_f32 v66, v66, v206, v238
	v_fma_f32 v67, v67, v207, v239
	v_fma_f32 v68, v68, v208, v240
	v_fma_f32 v69, v69, v209, v241
	global_store_dwordx4 v243, v[78:81], s[82:83] offset:0
	global_store_dwordx4 v243, v[74:77], s[82:83] offset:64
	global_store_dwordx4 v243, v[70:73], s[82:83] offset:128
	global_store_dwordx4 v243, v[66:69], s[82:83] offset:192
	v_add_u32_e32 v243, 0x10000, v243
	global_load_dwordx4 v[226:229], v242, s[36:37] offset:0
	global_load_dwordx4 v[230:233], v242, s[36:37] offset:64
	global_load_dwordx4 v[234:237], v242, s[36:37] offset:128
	global_load_dwordx4 v[238:241], v242, s[36:37] offset:192
	v_add_u32_e32 v242, 0x10000, v242
	s_waitcnt vmcnt(8)
	v_fma_f32 v62, v62, v194, v210
	v_fma_f32 v63, v63, v195, v211
	v_fma_f32 v64, v64, v196, v212
	v_fma_f32 v65, v65, v197, v213
	v_fma_f32 v58, v58, v198, v214
	v_fma_f32 v59, v59, v199, v215
	v_fma_f32 v60, v60, v200, v216
	v_fma_f32 v61, v61, v201, v217
	v_fma_f32 v54, v54, v202, v218
	v_fma_f32 v55, v55, v203, v219
	v_fma_f32 v56, v56, v204, v220
	v_fma_f32 v57, v57, v205, v221
	v_fma_f32 v50, v50, v206, v222
	v_fma_f32 v51, v51, v207, v223
	v_fma_f32 v52, v52, v208, v224
	v_fma_f32 v53, v53, v209, v225
	global_store_dwordx4 v243, v[62:65], s[82:83] offset:0
	global_store_dwordx4 v243, v[58:61], s[82:83] offset:64
	global_store_dwordx4 v243, v[54:57], s[82:83] offset:128
	global_store_dwordx4 v243, v[50:53], s[82:83] offset:192
	v_add_u32_e32 v243, 0x10000, v243
	global_load_dwordx4 v[210:213], v242, s[36:37] offset:0
	global_load_dwordx4 v[214:217], v242, s[36:37] offset:64
	global_load_dwordx4 v[218:221], v242, s[36:37] offset:128
	global_load_dwordx4 v[222:225], v242, s[36:37] offset:192
	v_add_u32_e32 v242, 0x10000, v242
	s_waitcnt vmcnt(8)
	v_fma_f32 v46, v46, v194, v226
	v_fma_f32 v47, v47, v195, v227
	v_fma_f32 v48, v48, v196, v228
	v_fma_f32 v49, v49, v197, v229
	v_fma_f32 v42, v42, v198, v230
	v_fma_f32 v43, v43, v199, v231
	v_fma_f32 v44, v44, v200, v232
	v_fma_f32 v45, v45, v201, v233
	v_fma_f32 v38, v38, v202, v234
	v_fma_f32 v39, v39, v203, v235
	v_fma_f32 v40, v40, v204, v236
	v_fma_f32 v41, v41, v205, v237
	v_fma_f32 v34, v34, v206, v238
	v_fma_f32 v35, v35, v207, v239
	v_fma_f32 v36, v36, v208, v240
	v_fma_f32 v37, v37, v209, v241
	global_store_dwordx4 v243, v[46:49], s[82:83] offset:0
	global_store_dwordx4 v243, v[42:45], s[82:83] offset:64
	global_store_dwordx4 v243, v[38:41], s[82:83] offset:128
	global_store_dwordx4 v243, v[34:37], s[82:83] offset:192
	v_add_u32_e32 v243, 0x10000, v243
	global_load_dwordx4 v[226:229], v242, s[36:37] offset:0
	global_load_dwordx4 v[230:233], v242, s[36:37] offset:64
	global_load_dwordx4 v[234:237], v242, s[36:37] offset:128
	global_load_dwordx4 v[238:241], v242, s[36:37] offset:192
	v_add_u32_e32 v242, 0x10000, v242
	s_waitcnt vmcnt(8)
	v_fma_f32 v30, v30, v194, v210
	v_fma_f32 v31, v31, v195, v211
	v_fma_f32 v32, v32, v196, v212
	v_fma_f32 v33, v33, v197, v213
	v_fma_f32 v26, v26, v198, v214
	v_fma_f32 v27, v27, v199, v215
	v_fma_f32 v28, v28, v200, v216
	v_fma_f32 v29, v29, v201, v217
	v_fma_f32 v22, v22, v202, v218
	v_fma_f32 v23, v23, v203, v219
	v_fma_f32 v24, v24, v204, v220
	v_fma_f32 v25, v25, v205, v221
	v_fma_f32 v18, v18, v206, v222
	v_fma_f32 v19, v19, v207, v223
	v_fma_f32 v20, v20, v208, v224
	v_fma_f32 v21, v21, v209, v225
	global_store_dwordx4 v243, v[30:33], s[82:83] offset:0
	global_store_dwordx4 v243, v[26:29], s[82:83] offset:64
	global_store_dwordx4 v243, v[22:25], s[82:83] offset:128
	global_store_dwordx4 v243, v[18:21], s[82:83] offset:192
	v_add_u32_e32 v243, 0x10000, v243
	s_waitcnt vmcnt(4)
	v_fma_f32 v14, v14, v194, v226
	v_fma_f32 v15, v15, v195, v227
	v_fma_f32 v16, v16, v196, v228
	v_fma_f32 v17, v17, v197, v229
	v_fma_f32 v10, v10, v198, v230
	v_fma_f32 v11, v11, v199, v231
	v_fma_f32 v12, v12, v200, v232
	v_fma_f32 v13, v13, v201, v233
	v_fma_f32 v6, v6, v202, v234
	v_fma_f32 v7, v7, v203, v235
	v_fma_f32 v8, v8, v204, v236
	v_fma_f32 v9, v9, v205, v237
	v_fma_f32 v2, v2, v206, v238
	v_fma_f32 v3, v3, v207, v239
	v_fma_f32 v4, v4, v208, v240
	v_fma_f32 v5, v5, v209, v241
	global_store_dwordx4 v243, v[14:17], s[82:83] offset:0
	global_store_dwordx4 v243, v[10:13], s[82:83] offset:64
	global_store_dwordx4 v243, v[6:9], s[82:83] offset:128
	global_store_dwordx4 v243, v[2:5], s[82:83] offset:192
	v_add_u32_e32 v243, 0x10000, v243
	s_mov_b64 s[10:11], exec
	s_branch .LBB0_1327
.Lop0_orig:
	s_and_saveexec_b64 s[12:13], vcc
	s_cbranch_execz .LBB0_1344
	v_ashrrev_i32_e32 v130, 12, v134
	v_add_u32_e32 v131, 0xffffc004, v134
	v_cmp_gt_i32_e32 vcc, s3, v134
	v_ashrrev_i32_e32 v135, 31, v134
	v_lshlrev_b64 v[136:137], 12, v[134:135]
	v_cndmask_b32_e32 v132, v131, v130, vcc
	v_mov_b64_e32 v[130:131], s[6:7]
	v_mad_i64_i32 v[130:131], s[0:1], v132, s17, v[130:131]
	v_lshl_add_u64 v[138:139], v[130:131], 0, v[0:1]
	global_load_dwordx4 v[130:133], v[138:139], off
	v_readlane_b32 s36, v192, 37
	v_lshlrev_b64 v[140:141], 10, v[134:135]
	v_lshl_add_u64 v[136:137], s[82:83], 0, v[136:137]
	v_readlane_b32 s37, v192, 38
	v_lshl_add_u64 v[136:137], v[136:137], 0, v[0:1]
	s_mov_b64 s[0:1], -1
	s_and_b64 vcc, exec, s[10:11]
	v_lshl_add_u64 v[140:141], v[140:141], 2, s[36:37]
	v_readlane_b32 s38, v192, 39
	v_readlane_b32 s39, v192, 40
	v_readlane_b32 s40, v192, 41
	v_readlane_b32 s41, v192, 42
	v_readlane_b32 s42, v192, 43
	v_readlane_b32 s43, v192, 44
	v_readlane_b32 s44, v192, 45
	v_readlane_b32 s45, v192, 46
	v_readlane_b32 s46, v192, 47
	v_readlane_b32 s47, v192, 48
	v_readlane_b32 s48, v192, 49
	v_readlane_b32 s49, v192, 50
	v_readlane_b32 s50, v192, 51
	v_readlane_b32 s51, v192, 52
	s_cbranch_vccz .LBB0_1335
	v_lshl_add_u64 v[144:145], v[140:141], 0, v[0:1]
	global_load_dwordx4 v[144:147], v[144:145], off
	s_mov_b64 s[0:1], 0
	s_waitcnt vmcnt(0)
	v_pk_fma_f32 v[144:145], v[126:127], v[130:131], v[144:145]
	v_pk_fma_f32 v[146:147], v[128:129], v[132:133], v[146:147]
	global_store_dwordx4 v[136:137], v[144:147], off

.LBB0_1665:
	s_waitcnt vmcnt(0)
	v_lshlrev_b32_e32 v0, 2, v166
	s_waitcnt lgkmcnt(0)
	s_barrier
	s_waitcnt lgkmcnt(0)
	v_lshl_or_b32 v140, s15, 7, v167
	v_lshl_or_b32 v0, s14, 6, v0
	v_add_u32_e32 v134, s22, v140
	v_or_b32_e32 v0, s12, v0
	v_cmp_gt_i32_e32 vcc, s20, v134
	v_lshlrev_b32_e32 v0, 2, v0
	s_cmp_eq_u64 s[10:11], 0
	s_cbranch_scc1 .Lop1_orig
	s_lshr_b32 s0, s22, 12
	s_mul_i32 s0, s0, s17
	s_add_u32 s0, s4, s0
	s_addc_u32 s1, s5, 0
	global_load_dwordx4 v[194:197], v0, s[0:1] offset:0
	global_load_dwordx4 v[198:201], v0, s[0:1] offset:64
	global_load_dwordx4 v[202:205], v0, s[0:1] offset:128
	global_load_dwordx4 v[206:209], v0, s[0:1] offset:192
	v_lshlrev_b32_e32 v242, 12, v134
	v_add_u32_e32 v242, v242, v0
	v_mov_b32_e32 v243, v242
	global_load_dwordx4 v[210:213], v242, s[82:83] offset:0
	global_load_dwordx4 v[214:217], v242, s[82:83] offset:64
	global_load_dwordx4 v[218:221], v242, s[82:83] offset:128
	global_load_dwordx4 v[222:225], v242, s[82:83] offset:192
	v_add_u32_e32 v242, 0x10000, v242
	global_load_dwordx4 v[226:229], v242, s[82:83] offset:0
	global_load_dwordx4 v[230:233], v242, s[82:83] offset:64
	global_load_dwordx4 v[234:237], v242, s[82:83] offset:128
	global_load_dwordx4 v[238:241], v242, s[82:83] offset:192
	v_add_u32_e32 v242, 0x10000, v242
	s_waitcnt vmcnt(4)
	v_fma_f32 v126, v126, v194, v210
	v_fma_f32 v127, v127, v195, v211
	v_fma_f32 v128, v128, v196, v212
	v_fma_f32 v129, v129, v197, v213
	v_fma_f32 v122, v122, v198, v214
	v_fma_f32 v123, v123, v199, v215
	v_fma_f32 v124, v124, v200, v216
	v_fma_f32 v125, v125, v201, v217
	v_fma_f32 v118, v118, v202, v218
	v_fma_f32 v119, v119, v203, v219
	v_fma_f32 v120, v120, v204, v220
	v_fma_f32 v121, v121, v205, v221
	v_fma_f32 v114, v114, v206, v222
	v_fma_f32 v115, v115, v207, v223
	v_fma_f32 v116, v116, v208, v224
	v_fma_f32 v117, v117, v209, v225
	global_store_dwordx4 v243, v[126:129], s[82:83] offset:0
	global_store_dwordx4 v243, v[122:125], s[82:83] offset:64
	global_store_dwordx4 v243, v[118:121], s[82:83] offset:128
	global_store_dwordx4 v243, v[114:117], s[82:83] offset:192
	v_add_u32_e32 v243, 0x10000, v243
	global_load_dwordx4 v[210:213], v242, s[82:83] offset:0
	global_load_dwordx4 v[214:217], v242, s[82:83] offset:64
	global_load_dwordx4 v[218:221], v242, s[82:83] offset:128
	global_load_dwordx4 v[222:225], v242, s[82:83] offset:192
	v_add_u32_e32 v242, 0x10000, v242
	s_waitcnt vmcnt(8)
	v_fma_f32 v110, v110, v194, v226
	v_fma_f32 v111, v111, v195, v227
	v_fma_f32 v112, v112, v196, v228
	v_fma_f32 v113, v113, v197, v229
	v_fma_f32 v106, v106, v198, v230
	v_fma_f32 v107, v107, v199, v231
	v_fma_f32 v108, v108, v200, v232
	v_fma_f32 v109, v109, v201, v233
	v_fma_f32 v102, v102, v202, v234
	v_fma_f32 v103, v103, v203, v235
	v_fma_f32 v104, v104, v204, v236
	v_fma_f32 v105, v105, v205, v237
	v_fma_f32 v98, v98, v206, v238
	v_fma_f32 v99, v99, v207, v239
	v_fma_f32 v100, v100, v208, v240
	v_fma_f32 v101, v101, v209, v241
	global_store_dwordx4 v243, v[110:113], s[82:83] offset:0
	global_store_dwordx4 v243, v[106:109], s[82:83] offset:64
	global_store_dwordx4 v243, v[102:105], s[82:83] offset:128
	global_store_dwordx4 v243, v[98:101], s[82:83] offset:192
	v_add_u32_e32 v243, 0x10000, v243
	global_load_dwordx4 v[226:229], v242, s[82:83] offset:0
	global_load_dwordx4 v[230:233], v242, s[82:83] offset:64
	global_load_dwordx4 v[234:237], v242, s[82:83] offset:128
	global_load_dwordx4 v[238:241], v242, s[82:83] offset:192
	v_add_u32_e32 v242, 0x10000, v242
	s_waitcnt vmcnt(8)
	v_fma_f32 v94, v94, v194, v210
	v_fma_f32 v95, v95, v195, v211
	v_fma_f32 v96, v96, v196, v212
	v_fma_f32 v97, v97, v197, v213
	v_fma_f32 v90, v90, v198, v214
	v_fma_f32 v91, v91, v199, v215
	v_fma_f32 v92, v92, v200, v216
	v_fma_f32 v93, v93, v201, v217
	v_fma_f32 v86, v86, v202, v218
	v_fma_f32 v87, v87, v203, v219
	v_fma_f32 v88, v88, v204, v220
	v_fma_f32 v89, v89, v205, v221
	v_fma_f32 v82, v82, v206, v222
	v_fma_f32 v83, v83, v207, v223
	v_fma_f32 v84, v84, v208, v224
	v_fma_f32 v85, v85, v209, v225
	global_store_dwordx4 v243, v[94:97], s[82:83] offset:0
	global_store_dwordx4 v243, v[90:93], s[82:83] offset:64
	global_store_dwordx4 v243, v[86:89], s[82:83] offset:128
	global_store_dwordx4 v243, v[82:85], s[82:83] offset:192
	v_add_u32_e32 v243, 0x10000, v243
	global_load_dwordx4 v[210:213], v242, s[82:83] offset:0
	global_load_dwordx4 v[214:217], v242, s[82:83] offset:64
	global_load_dwordx4 v[218:221], v242, s[82:83] offset:128
	global_load_dwordx4 v[222:225], v242, s[82:83] offset:192
	v_add_u32_e32 v242, 0x10000, v242
	s_waitcnt vmcnt(8)
	v_fma_f32 v78, v78, v194, v226
	v_fma_f32 v79, v79, v195, v227
	v_fma_f32 v80, v80, v196, v228
	v_fma_f32 v81, v81, v197, v229
	v_fma_f32 v74, v74, v198, v230
	v_fma_f32 v75, v75, v199, v231
	v_fma_f32 v76, v76, v200, v232
	v_fma_f32 v77, v77, v201, v233
	v_fma_f32 v70, v70, v202, v234
	v_fma_f32 v71, v71, v203, v235
	v_fma_f32 v72, v72, v204, v236
	v_fma_f32 v73, v73, v205, v237
	v_fma_f32 v66, v66, v206, v238
	v_fma_f32 v67, v67, v207, v239
	v_fma_f32 v68, v68, v208, v240
	v_fma_f32 v69, v69, v209, v241
	global_store_dwordx4 v243, v[78:81], s[82:83] offset:0
	global_store_dwordx4 v243, v[74:77], s[82:83] offset:64
	global_store_dwordx4 v243, v[70:73], s[82:83] offset:128
	global_store_dwordx4 v243, v[66:69], s[82:83] offset:192
	v_add_u32_e32 v243, 0x10000, v243
	global_load_dwordx4 v[226:229], v242, s[82:83] offset:0
	global_load_dwordx4 v[230:233], v242, s[82:83] offset:64
	global_load_dwordx4 v[234:237], v242, s[82:83] offset:128
	global_load_dwordx4 v[238:241], v242, s[82:83] offset:192
	v_add_u32_e32 v242, 0x10000, v242
	s_waitcnt vmcnt(8)
	v_fma_f32 v62, v62, v194, v210
	v_fma_f32 v63, v63, v195, v211
	v_fma_f32 v64, v64, v196, v212
	v_fma_f32 v65, v65, v197, v213
	v_fma_f32 v58, v58, v198, v214
	v_fma_f32 v59, v59, v199, v215
	v_fma_f32 v60, v60, v200, v216
	v_fma_f32 v61, v61, v201, v217
	v_fma_f32 v54, v54, v202, v218
	v_fma_f32 v55, v55, v203, v219
	v_fma_f32 v56, v56, v204, v220
	v_fma_f32 v57, v57, v205, v221
	v_fma_f32 v50, v50, v206, v222
	v_fma_f32 v51, v51, v207, v223
	v_fma_f32 v52, v52, v208, v224
	v_fma_f32 v53, v53, v209, v225
	global_store_dwordx4 v243, v[62:65], s[82:83] offset:0
	global_store_dwordx4 v243, v[58:61], s[82:83] offset:64
	global_store_dwordx4 v243, v[54:57], s[82:83] offset:128
	global_store_dwordx4 v243, v[50:53], s[82:83] offset:192
	v_add_u32_e32 v243, 0x10000, v243
	global_load_dwordx4 v[210:213], v242, s[82:83] offset:0
	global_load_dwordx4 v[214:217], v242, s[82:83] offset:64
	global_load_dwordx4 v[218:221], v242, s[82:83] offset:128
	global_load_dwordx4 v[222:225], v242, s[82:83] offset:192
	v_add_u32_e32 v242, 0x10000, v242
	s_waitcnt vmcnt(8)
	v_fma_f32 v46, v46, v194, v226
	v_fma_f32 v47, v47, v195, v227
	v_fma_f32 v48, v48, v196, v228
	v_fma_f32 v49, v49, v197, v229
	v_fma_f32 v42, v42, v198, v230
	v_fma_f32 v43, v43, v199, v231
	v_fma_f32 v44, v44, v200, v232
	v_fma_f32 v45, v45, v201, v233
	v_fma_f32 v38, v38, v202, v234
	v_fma_f32 v39, v39, v203, v235
	v_fma_f32 v40, v40, v204, v236
	v_fma_f32 v41, v41, v205, v237
	v_fma_f32 v34, v34, v206, v238
	v_fma_f32 v35, v35, v207, v239
	v_fma_f32 v36, v36, v208, v240
	v_fma_f32 v37, v37, v209, v241
	global_store_dwordx4 v243, v[46:49], s[82:83] offset:0
	global_store_dwordx4 v243, v[42:45], s[82:83] offset:64
	global_store_dwordx4 v243, v[38:41], s[82:83] offset:128
	global_store_dwordx4 v243, v[34:37], s[82:83] offset:192
	v_add_u32_e32 v243, 0x10000, v243
	global_load_dwordx4 v[226:229], v242, s[82:83] offset:0
	global_load_dwordx4 v[230:233], v242, s[82:83] offset:64
	global_load_dwordx4 v[234:237], v242, s[82:83] offset:128
	global_load_dwordx4 v[238:241], v242, s[82:83] offset:192
	v_add_u32_e32 v242, 0x10000, v242
	s_waitcnt vmcnt(8)
	v_fma_f32 v30, v30, v194, v210
	v_fma_f32 v31, v31, v195, v211
	v_fma_f32 v32, v32, v196, v212
	v_fma_f32 v33, v33, v197, v213
	v_fma_f32 v26, v26, v198, v214
	v_fma_f32 v27, v27, v199, v215
	v_fma_f32 v28, v28, v200, v216
	v_fma_f32 v29, v29, v201, v217
	v_fma_f32 v22, v22, v202, v218
	v_fma_f32 v23, v23, v203, v219
	v_fma_f32 v24, v24, v204, v220
	v_fma_f32 v25, v25, v205, v221
	v_fma_f32 v18, v18, v206, v222
	v_fma_f32 v19, v19, v207, v223
	v_fma_f32 v20, v20, v208, v224
	v_fma_f32 v21, v21, v209, v225
	global_store_dwordx4 v243, v[30:33], s[82:83] offset:0
	global_store_dwordx4 v243, v[26:29], s[82:83] offset:64
	global_store_dwordx4 v243, v[22:25], s[82:83] offset:128
	global_store_dwordx4 v243, v[18:21], s[82:83] offset:192
	v_add_u32_e32 v243, 0x10000, v243
	s_waitcnt vmcnt(4)
	v_fma_f32 v14, v14, v194, v226
	v_fma_f32 v15, v15, v195, v227
	v_fma_f32 v16, v16, v196, v228
	v_fma_f32 v17, v17, v197, v229
	v_fma_f32 v10, v10, v198, v230
	v_fma_f32 v11, v11, v199, v231
	v_fma_f32 v12, v12, v200, v232
	v_fma_f32 v13, v13, v201, v233
	v_fma_f32 v6, v6, v202, v234
	v_fma_f32 v7, v7, v203, v235
	v_fma_f32 v8, v8, v204, v236
	v_fma_f32 v9, v9, v205, v237
	v_fma_f32 v2, v2, v206, v238
	v_fma_f32 v3, v3, v207, v239
	v_fma_f32 v4, v4, v208, v240
	v_fma_f32 v5, v5, v209, v241
	global_store_dwordx4 v243, v[14:17], s[82:83] offset:0
	global_store_dwordx4 v243, v[10:13], s[82:83] offset:64
	global_store_dwordx4 v243, v[6:9], s[82:83] offset:128
	global_store_dwordx4 v243, v[2:5], s[82:83] offset:192
	v_add_u32_e32 v243, 0x10000, v243
	s_mov_b64 s[10:11], exec
	s_branch .LBB0_1660
.Lop1_orig:
	s_and_saveexec_b64 s[12:13], vcc
	s_cbranch_execz .LBB0_1677
	v_ashrrev_i32_e32 v130, 12, v134
	v_add_u32_e32 v131, 0xffffc004, v134
	v_cmp_gt_i32_e32 vcc, s3, v134
	v_ashrrev_i32_e32 v135, 31, v134
	v_lshlrev_b64 v[136:137], 12, v[134:135]
	v_cndmask_b32_e32 v132, v131, v130, vcc
	v_mov_b64_e32 v[130:131], s[4:5]
	v_mad_i64_i32 v[130:131], s[0:1], v132, s17, v[130:131]
	v_lshl_add_u64 v[138:139], v[130:131], 0, v[0:1]
	global_load_dwordx4 v[130:133], v[138:139], off
	v_lshl_add_u64 v[136:137], s[82:83], 0, v[136:137]
	v_lshl_add_u64 v[136:137], v[136:137], 0, v[0:1]
	s_mov_b64 s[0:1], -1
	s_and_b64 vcc, exec, s[10:11]
	s_cbranch_vccz .LBB0_1668
	global_load_dwordx4 v[142:145], v[136:137], off
	s_mov_b64 s[0:1], 0
	s_waitcnt vmcnt(0)
	v_pk_fma_f32 v[142:143], v[126:127], v[130:131], v[142:143]
	v_pk_fma_f32 v[144:145], v[128:129], v[132:133], v[144:145]
	global_store_dwordx4 v[136:137], v[142:145], off

.LBB0_2757:
	s_waitcnt vmcnt(0)
	v_lshlrev_b32_e32 v0, 2, v166
	s_waitcnt lgkmcnt(0)
	s_barrier
	s_waitcnt lgkmcnt(0)
	v_lshl_or_b32 v140, s13, 7, v167
	v_lshl_or_b32 v0, s12, 6, v0
	v_add_u32_e32 v134, s20, v140
	v_or_b32_e32 v0, s10, v0
	v_cmp_gt_i32_e32 vcc, s18, v134
	v_lshlrev_b32_e32 v0, 2, v0
	s_cmp_eq_u64 s[8:9], 0
	s_cbranch_scc1 .Lop2_orig
	s_lshr_b32 s0, s20, 12
	s_addk_i32 s0, 0x84
	s_mul_i32 s0, s0, s15
	s_add_u32 s0, s4, s0
	s_addc_u32 s1, s5, 0
	global_load_dwordx4 v[194:197], v0, s[0:1] offset:0
	global_load_dwordx4 v[198:201], v0, s[0:1] offset:64
	global_load_dwordx4 v[202:205], v0, s[0:1] offset:128
	global_load_dwordx4 v[206:209], v0, s[0:1] offset:192
	v_lshlrev_b32_e32 v242, 12, v134
	v_add_u32_e32 v242, v242, v0
	v_mov_b32_e32 v243, v242
	global_load_dwordx4 v[210:213], v242, s[82:83] offset:0
	global_load_dwordx4 v[214:217], v242, s[82:83] offset:64
	global_load_dwordx4 v[218:221], v242, s[82:83] offset:128
	global_load_dwordx4 v[222:225], v242, s[82:83] offset:192
	v_add_u32_e32 v242, 0x10000, v242
	global_load_dwordx4 v[226:229], v242, s[82:83] offset:0
	global_load_dwordx4 v[230:233], v242, s[82:83] offset:64
	global_load_dwordx4 v[234:237], v242, s[82:83] offset:128
	global_load_dwordx4 v[238:241], v242, s[82:83] offset:192
	v_add_u32_e32 v242, 0x10000, v242
	s_waitcnt vmcnt(4)
	v_fma_f32 v126, v126, v194, v210
	v_fma_f32 v127, v127, v195, v211
	v_fma_f32 v128, v128, v196, v212
	v_fma_f32 v129, v129, v197, v213
	v_fma_f32 v122, v122, v198, v214
	v_fma_f32 v123, v123, v199, v215
	v_fma_f32 v124, v124, v200, v216
	v_fma_f32 v125, v125, v201, v217
	v_fma_f32 v118, v118, v202, v218
	v_fma_f32 v119, v119, v203, v219
	v_fma_f32 v120, v120, v204, v220
	v_fma_f32 v121, v121, v205, v221
	v_fma_f32 v114, v114, v206, v222
	v_fma_f32 v115, v115, v207, v223
	v_fma_f32 v116, v116, v208, v224
	v_fma_f32 v117, v117, v209, v225
	global_store_dwordx4 v243, v[126:129], s[82:83] offset:0
	global_store_dwordx4 v243, v[122:125], s[82:83] offset:64
	global_store_dwordx4 v243, v[118:121], s[82:83] offset:128
	global_store_dwordx4 v243, v[114:117], s[82:83] offset:192
	v_add_u32_e32 v243, 0x10000, v243
	global_load_dwordx4 v[210:213], v242, s[82:83] offset:0
	global_load_dwordx4 v[214:217], v242, s[82:83] offset:64
	global_load_dwordx4 v[218:221], v242, s[82:83] offset:128
	global_load_dwordx4 v[222:225], v242, s[82:83] offset:192
	v_add_u32_e32 v242, 0x10000, v242
	s_waitcnt vmcnt(8)
	v_fma_f32 v110, v110, v194, v226
	v_fma_f32 v111, v111, v195, v227
	v_fma_f32 v112, v112, v196, v228
	v_fma_f32 v113, v113, v197, v229
	v_fma_f32 v106, v106, v198, v230
	v_fma_f32 v107, v107, v199, v231
	v_fma_f32 v108, v108, v200, v232
	v_fma_f32 v109, v109, v201, v233
	v_fma_f32 v102, v102, v202, v234
	v_fma_f32 v103, v103, v203, v235
	v_fma_f32 v104, v104, v204, v236
	v_fma_f32 v105, v105, v205, v237
	v_fma_f32 v98, v98, v206, v238
	v_fma_f32 v99, v99, v207, v239
	v_fma_f32 v100, v100, v208, v240
	v_fma_f32 v101, v101, v209, v241
	global_store_dwordx4 v243, v[110:113], s[82:83] offset:0
	global_store_dwordx4 v243, v[106:109], s[82:83] offset:64
	global_store_dwordx4 v243, v[102:105], s[82:83] offset:128
	global_store_dwordx4 v243, v[98:101], s[82:83] offset:192
	v_add_u32_e32 v243, 0x10000, v243
	global_load_dwordx4 v[226:229], v242, s[82:83] offset:0
	global_load_dwordx4 v[230:233], v242, s[82:83] offset:64
	global_load_dwordx4 v[234:237], v242, s[82:83] offset:128
	global_load_dwordx4 v[238:241], v242, s[82:83] offset:192
	v_add_u32_e32 v242, 0x10000, v242
	s_waitcnt vmcnt(8)
	v_fma_f32 v94, v94, v194, v210
	v_fma_f32 v95, v95, v195, v211
	v_fma_f32 v96, v96, v196, v212
	v_fma_f32 v97, v97, v197, v213
	v_fma_f32 v90, v90, v198, v214
	v_fma_f32 v91, v91, v199, v215
	v_fma_f32 v92, v92, v200, v216
	v_fma_f32 v93, v93, v201, v217
	v_fma_f32 v86, v86, v202, v218
	v_fma_f32 v87, v87, v203, v219
	v_fma_f32 v88, v88, v204, v220
	v_fma_f32 v89, v89, v205, v221
	v_fma_f32 v82, v82, v206, v222
	v_fma_f32 v83, v83, v207, v223
	v_fma_f32 v84, v84, v208, v224
	v_fma_f32 v85, v85, v209, v225
	global_store_dwordx4 v243, v[94:97], s[82:83] offset:0
	global_store_dwordx4 v243, v[90:93], s[82:83] offset:64
	global_store_dwordx4 v243, v[86:89], s[82:83] offset:128
	global_store_dwordx4 v243, v[82:85], s[82:83] offset:192
	v_add_u32_e32 v243, 0x10000, v243
	global_load_dwordx4 v[210:213], v242, s[82:83] offset:0
	global_load_dwordx4 v[214:217], v242, s[82:83] offset:64
	global_load_dwordx4 v[218:221], v242, s[82:83] offset:128
	global_load_dwordx4 v[222:225], v242, s[82:83] offset:192
	v_add_u32_e32 v242, 0x10000, v242
	s_waitcnt vmcnt(8)
	v_fma_f32 v78, v78, v194, v226
	v_fma_f32 v79, v79, v195, v227
	v_fma_f32 v80, v80, v196, v228
	v_fma_f32 v81, v81, v197, v229
	v_fma_f32 v74, v74, v198, v230
	v_fma_f32 v75, v75, v199, v231
	v_fma_f32 v76, v76, v200, v232
	v_fma_f32 v77, v77, v201, v233
	v_fma_f32 v70, v70, v202, v234
	v_fma_f32 v71, v71, v203, v235
	v_fma_f32 v72, v72, v204, v236
	v_fma_f32 v73, v73, v205, v237
	v_fma_f32 v66, v66, v206, v238
	v_fma_f32 v67, v67, v207, v239
	v_fma_f32 v68, v68, v208, v240
	v_fma_f32 v69, v69, v209, v241
	global_store_dwordx4 v243, v[78:81], s[82:83] offset:0
	global_store_dwordx4 v243, v[74:77], s[82:83] offset:64
	global_store_dwordx4 v243, v[70:73], s[82:83] offset:128
	global_store_dwordx4 v243, v[66:69], s[82:83] offset:192
	v_add_u32_e32 v243, 0x10000, v243
	global_load_dwordx4 v[226:229], v242, s[82:83] offset:0
	global_load_dwordx4 v[230:233], v242, s[82:83] offset:64
	global_load_dwordx4 v[234:237], v242, s[82:83] offset:128
	global_load_dwordx4 v[238:241], v242, s[82:83] offset:192
	v_add_u32_e32 v242, 0x10000, v242
	s_waitcnt vmcnt(8)
	v_fma_f32 v62, v62, v194, v210
	v_fma_f32 v63, v63, v195, v211
	v_fma_f32 v64, v64, v196, v212
	v_fma_f32 v65, v65, v197, v213
	v_fma_f32 v58, v58, v198, v214
	v_fma_f32 v59, v59, v199, v215
	v_fma_f32 v60, v60, v200, v216
	v_fma_f32 v61, v61, v201, v217
	v_fma_f32 v54, v54, v202, v218
	v_fma_f32 v55, v55, v203, v219
	v_fma_f32 v56, v56, v204, v220
	v_fma_f32 v57, v57, v205, v221
	v_fma_f32 v50, v50, v206, v222
	v_fma_f32 v51, v51, v207, v223
	v_fma_f32 v52, v52, v208, v224
	v_fma_f32 v53, v53, v209, v225
	global_store_dwordx4 v243, v[62:65], s[82:83] offset:0
	global_store_dwordx4 v243, v[58:61], s[82:83] offset:64
	global_store_dwordx4 v243, v[54:57], s[82:83] offset:128
	global_store_dwordx4 v243, v[50:53], s[82:83] offset:192
	v_add_u32_e32 v243, 0x10000, v243
	global_load_dwordx4 v[210:213], v242, s[82:83] offset:0
	global_load_dwordx4 v[214:217], v242, s[82:83] offset:64
	global_load_dwordx4 v[218:221], v242, s[82:83] offset:128
	global_load_dwordx4 v[222:225], v242, s[82:83] offset:192
	v_add_u32_e32 v242, 0x10000, v242
	s_waitcnt vmcnt(8)
	v_fma_f32 v46, v46, v194, v226
	v_fma_f32 v47, v47, v195, v227
	v_fma_f32 v48, v48, v196, v228
	v_fma_f32 v49, v49, v197, v229
	v_fma_f32 v42, v42, v198, v230
	v_fma_f32 v43, v43, v199, v231
	v_fma_f32 v44, v44, v200, v232
	v_fma_f32 v45, v45, v201, v233
	v_fma_f32 v38, v38, v202, v234
	v_fma_f32 v39, v39, v203, v235
	v_fma_f32 v40, v40, v204, v236
	v_fma_f32 v41, v41, v205, v237
	v_fma_f32 v34, v34, v206, v238
	v_fma_f32 v35, v35, v207, v239
	v_fma_f32 v36, v36, v208, v240
	v_fma_f32 v37, v37, v209, v241
	global_store_dwordx4 v243, v[46:49], s[82:83] offset:0
	global_store_dwordx4 v243, v[42:45], s[82:83] offset:64
	global_store_dwordx4 v243, v[38:41], s[82:83] offset:128
	global_store_dwordx4 v243, v[34:37], s[82:83] offset:192
	v_add_u32_e32 v243, 0x10000, v243
	global_load_dwordx4 v[226:229], v242, s[82:83] offset:0
	global_load_dwordx4 v[230:233], v242, s[82:83] offset:64
	global_load_dwordx4 v[234:237], v242, s[82:83] offset:128
	global_load_dwordx4 v[238:241], v242, s[82:83] offset:192
	v_add_u32_e32 v242, 0x10000, v242
	s_waitcnt vmcnt(8)
	v_fma_f32 v30, v30, v194, v210
	v_fma_f32 v31, v31, v195, v211
	v_fma_f32 v32, v32, v196, v212
	v_fma_f32 v33, v33, v197, v213
	v_fma_f32 v26, v26, v198, v214
	v_fma_f32 v27, v27, v199, v215
	v_fma_f32 v28, v28, v200, v216
	v_fma_f32 v29, v29, v201, v217
	v_fma_f32 v22, v22, v202, v218
	v_fma_f32 v23, v23, v203, v219
	v_fma_f32 v24, v24, v204, v220
	v_fma_f32 v25, v25, v205, v221
	v_fma_f32 v18, v18, v206, v222
	v_fma_f32 v19, v19, v207, v223
	v_fma_f32 v20, v20, v208, v224
	v_fma_f32 v21, v21, v209, v225
	global_store_dwordx4 v243, v[30:33], s[82:83] offset:0
	global_store_dwordx4 v243, v[26:29], s[82:83] offset:64
	global_store_dwordx4 v243, v[22:25], s[82:83] offset:128
	global_store_dwordx4 v243, v[18:21], s[82:83] offset:192
	v_add_u32_e32 v243, 0x10000, v243
	s_waitcnt vmcnt(4)
	v_fma_f32 v14, v14, v194, v226
	v_fma_f32 v15, v15, v195, v227
	v_fma_f32 v16, v16, v196, v228
	v_fma_f32 v17, v17, v197, v229
	v_fma_f32 v10, v10, v198, v230
	v_fma_f32 v11, v11, v199, v231
	v_fma_f32 v12, v12, v200, v232
	v_fma_f32 v13, v13, v201, v233
	v_fma_f32 v6, v6, v202, v234
	v_fma_f32 v7, v7, v203, v235
	v_fma_f32 v8, v8, v204, v236
	v_fma_f32 v9, v9, v205, v237
	v_fma_f32 v2, v2, v206, v238
	v_fma_f32 v3, v3, v207, v239
	v_fma_f32 v4, v4, v208, v240
	v_fma_f32 v5, v5, v209, v241
	global_store_dwordx4 v243, v[14:17], s[82:83] offset:0
	global_store_dwordx4 v243, v[10:13], s[82:83] offset:64
	global_store_dwordx4 v243, v[6:9], s[82:83] offset:128
	global_store_dwordx4 v243, v[2:5], s[82:83] offset:192
	v_add_u32_e32 v243, 0x10000, v243
	s_mov_b64 s[8:9], exec
	s_branch .LBB0_2752
.Lop2_orig:
	s_and_saveexec_b64 s[10:11], vcc
	s_cbranch_execz .LBB0_2769
	v_ashrrev_i32_e32 v130, 12, v134
	v_add_u32_e32 v131, 0xffffc004, v134
	v_cmp_gt_i32_e32 vcc, s3, v134
	v_ashrrev_i32_e32 v135, 31, v134
	v_lshlrev_b64 v[136:137], 12, v[134:135]
	v_cndmask_b32_e32 v130, v131, v130, vcc
	v_add_u32_e32 v132, 0x84, v130
	v_mov_b64_e32 v[130:131], s[4:5]
	v_mad_i64_i32 v[130:131], s[0:1], v132, s15, v[130:131]
	v_lshl_add_u64 v[138:139], v[130:131], 0, v[0:1]
	global_load_dwordx4 v[130:133], v[138:139], off
	v_lshl_add_u64 v[136:137], s[82:83], 0, v[136:137]
	v_lshl_add_u64 v[136:137], v[136:137], 0, v[0:1]
	s_mov_b64 s[0:1], -1
	s_and_b64 vcc, exec, s[8:9]
	s_cbranch_vccz .LBB0_2760
	global_load_dwordx4 v[142:145], v[136:137], off
	s_mov_b64 s[0:1], 0
	s_waitcnt vmcnt(0)
	v_pk_fma_f32 v[142:143], v[126:127], v[130:131], v[142:143]
	v_pk_fma_f32 v[144:145], v[128:129], v[132:133], v[144:145]
	global_store_dwordx4 v[136:137], v[142:145], off

.LBB0_3090:
	s_waitcnt vmcnt(0)
	v_lshlrev_b32_e32 v0, 2, v166
	s_waitcnt lgkmcnt(0)
	s_barrier
	s_waitcnt lgkmcnt(0)
	v_lshl_or_b32 v140, s15, 7, v167
	v_lshl_or_b32 v0, s14, 6, v0
	v_add_u32_e32 v134, s21, v140
	v_or_b32_e32 v0, s12, v0
	v_cmp_gt_i32_e32 vcc, s20, v134
	v_lshlrev_b32_e32 v0, 2, v0
	s_cmp_eq_u64 s[10:11], 0
	s_cbranch_scc1 .Lop3_orig
	s_lshr_b32 s0, s21, 12
	s_addk_i32 s0, 0x84
	s_mul_i32 s0, s0, s17
	s_add_u32 s0, s4, s0
	s_addc_u32 s1, s5, 0
	global_load_dwordx4 v[194:197], v0, s[0:1] offset:0
	global_load_dwordx4 v[198:201], v0, s[0:1] offset:64
	global_load_dwordx4 v[202:205], v0, s[0:1] offset:128
	global_load_dwordx4 v[206:209], v0, s[0:1] offset:192
	v_lshlrev_b32_e32 v242, 12, v134
	v_add_u32_e32 v242, v242, v0
	v_mov_b32_e32 v243, v242
	global_load_dwordx4 v[210:213], v242, s[82:83] offset:0
	global_load_dwordx4 v[214:217], v242, s[82:83] offset:64
	global_load_dwordx4 v[218:221], v242, s[82:83] offset:128
	global_load_dwordx4 v[222:225], v242, s[82:83] offset:192
	v_add_u32_e32 v242, 0x10000, v242
	global_load_dwordx4 v[226:229], v242, s[82:83] offset:0
	global_load_dwordx4 v[230:233], v242, s[82:83] offset:64
	global_load_dwordx4 v[234:237], v242, s[82:83] offset:128
	global_load_dwordx4 v[238:241], v242, s[82:83] offset:192
	v_add_u32_e32 v242, 0x10000, v242
	s_waitcnt vmcnt(4)
	v_fma_f32 v126, v126, v194, v210
	v_fma_f32 v127, v127, v195, v211
	v_fma_f32 v128, v128, v196, v212
	v_fma_f32 v129, v129, v197, v213
	v_fma_f32 v122, v122, v198, v214
	v_fma_f32 v123, v123, v199, v215
	v_fma_f32 v124, v124, v200, v216
	v_fma_f32 v125, v125, v201, v217
	v_fma_f32 v118, v118, v202, v218
	v_fma_f32 v119, v119, v203, v219
	v_fma_f32 v120, v120, v204, v220
	v_fma_f32 v121, v121, v205, v221
	v_fma_f32 v114, v114, v206, v222
	v_fma_f32 v115, v115, v207, v223
	v_fma_f32 v116, v116, v208, v224
	v_fma_f32 v117, v117, v209, v225
	global_store_dwordx4 v243, v[126:129], s[82:83] offset:0
	global_store_dwordx4 v243, v[122:125], s[82:83] offset:64
	global_store_dwordx4 v243, v[118:121], s[82:83] offset:128
	global_store_dwordx4 v243, v[114:117], s[82:83] offset:192
	v_add_u32_e32 v243, 0x10000, v243
	global_load_dwordx4 v[210:213], v242, s[82:83] offset:0
	global_load_dwordx4 v[214:217], v242, s[82:83] offset:64
	global_load_dwordx4 v[218:221], v242, s[82:83] offset:128
	global_load_dwordx4 v[222:225], v242, s[82:83] offset:192
	v_add_u32_e32 v242, 0x10000, v242
	s_waitcnt vmcnt(8)
	v_fma_f32 v110, v110, v194, v226
	v_fma_f32 v111, v111, v195, v227
	v_fma_f32 v112, v112, v196, v228
	v_fma_f32 v113, v113, v197, v229
	v_fma_f32 v106, v106, v198, v230
	v_fma_f32 v107, v107, v199, v231
	v_fma_f32 v108, v108, v200, v232
	v_fma_f32 v109, v109, v201, v233
	v_fma_f32 v102, v102, v202, v234
	v_fma_f32 v103, v103, v203, v235
	v_fma_f32 v104, v104, v204, v236
	v_fma_f32 v105, v105, v205, v237
	v_fma_f32 v98, v98, v206, v238
	v_fma_f32 v99, v99, v207, v239
	v_fma_f32 v100, v100, v208, v240
	v_fma_f32 v101, v101, v209, v241
	global_store_dwordx4 v243, v[110:113], s[82:83] offset:0
	global_store_dwordx4 v243, v[106:109], s[82:83] offset:64
	global_store_dwordx4 v243, v[102:105], s[82:83] offset:128
	global_store_dwordx4 v243, v[98:101], s[82:83] offset:192
	v_add_u32_e32 v243, 0x10000, v243
	global_load_dwordx4 v[226:229], v242, s[82:83] offset:0
	global_load_dwordx4 v[230:233], v242, s[82:83] offset:64
	global_load_dwordx4 v[234:237], v242, s[82:83] offset:128
	global_load_dwordx4 v[238:241], v242, s[82:83] offset:192
	v_add_u32_e32 v242, 0x10000, v242
	s_waitcnt vmcnt(8)
	v_fma_f32 v94, v94, v194, v210
	v_fma_f32 v95, v95, v195, v211
	v_fma_f32 v96, v96, v196, v212
	v_fma_f32 v97, v97, v197, v213
	v_fma_f32 v90, v90, v198, v214
	v_fma_f32 v91, v91, v199, v215
	v_fma_f32 v92, v92, v200, v216
	v_fma_f32 v93, v93, v201, v217
	v_fma_f32 v86, v86, v202, v218
	v_fma_f32 v87, v87, v203, v219
	v_fma_f32 v88, v88, v204, v220
	v_fma_f32 v89, v89, v205, v221
	v_fma_f32 v82, v82, v206, v222
	v_fma_f32 v83, v83, v207, v223
	v_fma_f32 v84, v84, v208, v224
	v_fma_f32 v85, v85, v209, v225
	global_store_dwordx4 v243, v[94:97], s[82:83] offset:0
	global_store_dwordx4 v243, v[90:93], s[82:83] offset:64
	global_store_dwordx4 v243, v[86:89], s[82:83] offset:128
	global_store_dwordx4 v243, v[82:85], s[82:83] offset:192
	v_add_u32_e32 v243, 0x10000, v243
	global_load_dwordx4 v[210:213], v242, s[82:83] offset:0
	global_load_dwordx4 v[214:217], v242, s[82:83] offset:64
	global_load_dwordx4 v[218:221], v242, s[82:83] offset:128
	global_load_dwordx4 v[222:225], v242, s[82:83] offset:192
	v_add_u32_e32 v242, 0x10000, v242
	s_waitcnt vmcnt(8)
	v_fma_f32 v78, v78, v194, v226
	v_fma_f32 v79, v79, v195, v227
	v_fma_f32 v80, v80, v196, v228
	v_fma_f32 v81, v81, v197, v229
	v_fma_f32 v74, v74, v198, v230
	v_fma_f32 v75, v75, v199, v231
	v_fma_f32 v76, v76, v200, v232
	v_fma_f32 v77, v77, v201, v233
	v_fma_f32 v70, v70, v202, v234
	v_fma_f32 v71, v71, v203, v235
	v_fma_f32 v72, v72, v204, v236
	v_fma_f32 v73, v73, v205, v237
	v_fma_f32 v66, v66, v206, v238
	v_fma_f32 v67, v67, v207, v239
	v_fma_f32 v68, v68, v208, v240
	v_fma_f32 v69, v69, v209, v241
	global_store_dwordx4 v243, v[78:81], s[82:83] offset:0
	global_store_dwordx4 v243, v[74:77], s[82:83] offset:64
	global_store_dwordx4 v243, v[70:73], s[82:83] offset:128
	global_store_dwordx4 v243, v[66:69], s[82:83] offset:192
	v_add_u32_e32 v243, 0x10000, v243
	global_load_dwordx4 v[226:229], v242, s[82:83] offset:0
	global_load_dwordx4 v[230:233], v242, s[82:83] offset:64
	global_load_dwordx4 v[234:237], v242, s[82:83] offset:128
	global_load_dwordx4 v[238:241], v242, s[82:83] offset:192
	v_add_u32_e32 v242, 0x10000, v242
	s_waitcnt vmcnt(8)
	v_fma_f32 v62, v62, v194, v210
	v_fma_f32 v63, v63, v195, v211
	v_fma_f32 v64, v64, v196, v212
	v_fma_f32 v65, v65, v197, v213
	v_fma_f32 v58, v58, v198, v214
	v_fma_f32 v59, v59, v199, v215
	v_fma_f32 v60, v60, v200, v216
	v_fma_f32 v61, v61, v201, v217
	v_fma_f32 v54, v54, v202, v218
	v_fma_f32 v55, v55, v203, v219
	v_fma_f32 v56, v56, v204, v220
	v_fma_f32 v57, v57, v205, v221
	v_fma_f32 v50, v50, v206, v222
	v_fma_f32 v51, v51, v207, v223
	v_fma_f32 v52, v52, v208, v224
	v_fma_f32 v53, v53, v209, v225
	global_store_dwordx4 v243, v[62:65], s[82:83] offset:0
	global_store_dwordx4 v243, v[58:61], s[82:83] offset:64
	global_store_dwordx4 v243, v[54:57], s[82:83] offset:128
	global_store_dwordx4 v243, v[50:53], s[82:83] offset:192
	v_add_u32_e32 v243, 0x10000, v243
	global_load_dwordx4 v[210:213], v242, s[82:83] offset:0
	global_load_dwordx4 v[214:217], v242, s[82:83] offset:64
	global_load_dwordx4 v[218:221], v242, s[82:83] offset:128
	global_load_dwordx4 v[222:225], v242, s[82:83] offset:192
	v_add_u32_e32 v242, 0x10000, v242
	s_waitcnt vmcnt(8)
	v_fma_f32 v46, v46, v194, v226
	v_fma_f32 v47, v47, v195, v227
	v_fma_f32 v48, v48, v196, v228
	v_fma_f32 v49, v49, v197, v229
	v_fma_f32 v42, v42, v198, v230
	v_fma_f32 v43, v43, v199, v231
	v_fma_f32 v44, v44, v200, v232
	v_fma_f32 v45, v45, v201, v233
	v_fma_f32 v38, v38, v202, v234
	v_fma_f32 v39, v39, v203, v235
	v_fma_f32 v40, v40, v204, v236
	v_fma_f32 v41, v41, v205, v237
	v_fma_f32 v34, v34, v206, v238
	v_fma_f32 v35, v35, v207, v239
	v_fma_f32 v36, v36, v208, v240
	v_fma_f32 v37, v37, v209, v241
	global_store_dwordx4 v243, v[46:49], s[82:83] offset:0
	global_store_dwordx4 v243, v[42:45], s[82:83] offset:64
	global_store_dwordx4 v243, v[38:41], s[82:83] offset:128
	global_store_dwordx4 v243, v[34:37], s[82:83] offset:192
	v_add_u32_e32 v243, 0x10000, v243
	global_load_dwordx4 v[226:229], v242, s[82:83] offset:0
	global_load_dwordx4 v[230:233], v242, s[82:83] offset:64
	global_load_dwordx4 v[234:237], v242, s[82:83] offset:128
	global_load_dwordx4 v[238:241], v242, s[82:83] offset:192
	v_add_u32_e32 v242, 0x10000, v242
	s_waitcnt vmcnt(8)
	v_fma_f32 v30, v30, v194, v210
	v_fma_f32 v31, v31, v195, v211
	v_fma_f32 v32, v32, v196, v212
	v_fma_f32 v33, v33, v197, v213
	v_fma_f32 v26, v26, v198, v214
	v_fma_f32 v27, v27, v199, v215
	v_fma_f32 v28, v28, v200, v216
	v_fma_f32 v29, v29, v201, v217
	v_fma_f32 v22, v22, v202, v218
	v_fma_f32 v23, v23, v203, v219
	v_fma_f32 v24, v24, v204, v220
	v_fma_f32 v25, v25, v205, v221
	v_fma_f32 v18, v18, v206, v222
	v_fma_f32 v19, v19, v207, v223
	v_fma_f32 v20, v20, v208, v224
	v_fma_f32 v21, v21, v209, v225
	global_store_dwordx4 v243, v[30:33], s[82:83] offset:0
	global_store_dwordx4 v243, v[26:29], s[82:83] offset:64
	global_store_dwordx4 v243, v[22:25], s[82:83] offset:128
	global_store_dwordx4 v243, v[18:21], s[82:83] offset:192
	v_add_u32_e32 v243, 0x10000, v243
	s_waitcnt vmcnt(4)
	v_fma_f32 v14, v14, v194, v226
	v_fma_f32 v15, v15, v195, v227
	v_fma_f32 v16, v16, v196, v228
	v_fma_f32 v17, v17, v197, v229
	v_fma_f32 v10, v10, v198, v230
	v_fma_f32 v11, v11, v199, v231
	v_fma_f32 v12, v12, v200, v232
	v_fma_f32 v13, v13, v201, v233
	v_fma_f32 v6, v6, v202, v234
	v_fma_f32 v7, v7, v203, v235
	v_fma_f32 v8, v8, v204, v236
	v_fma_f32 v9, v9, v205, v237
	v_fma_f32 v2, v2, v206, v238
	v_fma_f32 v3, v3, v207, v239
	v_fma_f32 v4, v4, v208, v240
	v_fma_f32 v5, v5, v209, v241
	global_store_dwordx4 v243, v[14:17], s[82:83] offset:0
	global_store_dwordx4 v243, v[10:13], s[82:83] offset:64
	global_store_dwordx4 v243, v[6:9], s[82:83] offset:128
	global_store_dwordx4 v243, v[2:5], s[82:83] offset:192
	v_add_u32_e32 v243, 0x10000, v243
	s_mov_b64 s[10:11], exec
	s_branch .LBB0_3085
.Lop3_orig:
	s_and_saveexec_b64 s[12:13], vcc
	s_cbranch_execz .LBB0_3102
	v_ashrrev_i32_e32 v130, 12, v134
	v_add_u32_e32 v131, 0xffffc004, v134
	v_cmp_gt_i32_e32 vcc, s3, v134
	v_ashrrev_i32_e32 v135, 31, v134
	v_lshlrev_b64 v[136:137], 12, v[134:135]
	v_cndmask_b32_e32 v130, v131, v130, vcc
	v_add_u32_e32 v132, 0x84, v130
	v_mov_b64_e32 v[130:131], s[4:5]
	v_mad_i64_i32 v[130:131], s[0:1], v132, s17, v[130:131]
	v_lshl_add_u64 v[138:139], v[130:131], 0, v[0:1]
	global_load_dwordx4 v[130:133], v[138:139], off
	v_lshl_add_u64 v[136:137], s[82:83], 0, v[136:137]
	v_lshl_add_u64 v[136:137], v[136:137], 0, v[0:1]
	s_mov_b64 s[0:1], -1
	s_and_b64 vcc, exec, s[10:11]
	s_cbranch_vccz .LBB0_3093
	global_load_dwordx4 v[142:145], v[136:137], off
	s_mov_b64 s[0:1], 0
	s_waitcnt vmcnt(0)
	v_pk_fma_f32 v[142:143], v[126:127], v[130:131], v[142:143]
	v_pk_fma_f32 v[144:145], v[128:129], v[132:133], v[144:145]
	global_store_dwordx4 v[136:137], v[142:145], off
